# v11 + LDS read ring (register rotation) in latent retention tile loop
# speedup vs baseline: 1.0049x; 1.0049x over previous
.LBB0_423:
	ds_read_b128 v[224:227], v219
	ds_read_b128 v[228:231], v213
	ds_read_b128 v[232:235], v219 offset:32
	ds_read_b128 v[236:239], v213 offset:32
	ds_read_b128 v[240:243], v219 offset:64
	ds_read_b128 v[244:247], v213 offset:64
	s_min_u32 s10, s9, 13
	v_lshl_add_u32 v94, s10, 6, v167
	s_waitcnt lgkmcnt(4)
	v_mfma_f32_32x32x16_bf16 v[98:113], v[224:227], v[228:231], 0
	ds_read_b128 v[224:227], v219 offset:96
	ds_read_b128 v[228:231], v213 offset:96
	v_mul_u32_u24_e32 v168, 0x9800, v94
	s_waitcnt lgkmcnt(4)
	v_mfma_f32_32x32x16_bf16 v[98:113], v[232:235], v[236:239], v[98:113]
	ds_read_b128 v[232:235], v219 offset:128
	ds_read_b128 v[236:239], v213 offset:128
	s_add_i32 s24, s44, s37
	s_waitcnt lgkmcnt(4)
	v_mfma_f32_32x32x16_bf16 v[98:113], v[240:243], v[244:247], v[98:113]
	ds_read_b128 v[240:243], v219 offset:160
	ds_read_b128 v[244:247], v213 offset:160
	v_add_u32_e32 v94, s37, v2
	s_cmp_lt_u32 s9, s36
	s_waitcnt lgkmcnt(4)
	v_mfma_f32_32x32x16_bf16 v[98:113], v[224:227], v[228:231], v[98:113]
	ds_read_b128 v[224:227], v219 offset:192
	ds_read_b128 v[228:231], v213 offset:192
	v_subrev_u32_e32 v94, 63, v94
	s_waitcnt lgkmcnt(4)
	v_mfma_f32_32x32x16_bf16 v[98:113], v[232:235], v[236:239], v[98:113]
	ds_read_b128 v[232:235], v219 offset:224
	ds_read_b128 v[236:239], v213 offset:224
	s_cselect_b64 vcc, -1, 0
	s_waitcnt lgkmcnt(4)
	v_mfma_f32_32x32x16_bf16 v[98:113], v[240:243], v[244:247], v[98:113]
	ds_read_b128 v[240:243], v219 offset:256
	ds_read_b128 v[244:247], v213 offset:256
	v_cndmask_b32_e32 v114, v81, v197, vcc
	s_and_b64 s[10:11], vcc, exec
	s_waitcnt lgkmcnt(4)
	v_mfma_f32_32x32x16_bf16 v[98:113], v[224:227], v[228:231], v[98:113]
	ds_read_b128 v[224:227], v219 offset:288
	ds_read_b128 v[228:231], v213 offset:288
	s_cselect_b32 s10, 0, 0x100
	s_waitcnt lgkmcnt(4)
	v_mfma_f32_32x32x16_bf16 v[98:113], v[232:235], v[236:239], v[98:113]
	ds_read_b128 v[232:235], v219 offset:320
	ds_read_b128 v[236:239], v213 offset:320
	s_cmp_lg_u32 s24, 0
	s_waitcnt lgkmcnt(4)
	v_mfma_f32_32x32x16_bf16 v[98:113], v[240:243], v[244:247], v[98:113]
	ds_read_b128 v[240:243], v219 offset:352
	ds_read_b128 v[244:247], v213 offset:352
	s_cselect_b64 s[86:87], -1, 0
	s_cmp_eq_u32 s24, 0
	s_waitcnt lgkmcnt(4)
	v_mfma_f32_32x32x16_bf16 v[98:113], v[224:227], v[228:231], v[98:113]
	ds_read_b128 v[224:227], v219 offset:384
	ds_read_b128 v[228:231], v213 offset:384
	v_lshl_add_u64 v[82:83], v[170:171], 0, v[168:169]
	s_waitcnt lgkmcnt(4)
	v_mfma_f32_32x32x16_bf16 v[98:113], v[232:235], v[236:239], v[98:113]
	ds_read_b128 v[232:235], v219 offset:416
	ds_read_b128 v[236:239], v213 offset:416
	global_load_dword v251, v[82:83], off
	s_waitcnt lgkmcnt(4)
	v_mfma_f32_32x32x16_bf16 v[98:113], v[240:243], v[244:247], v[98:113]
	ds_read_b128 v[240:243], v219 offset:448
	ds_read_b128 v[244:247], v213 offset:448
	v_cndmask_b32_e32 v86, v203, v94, vcc
	v_cvt_f32_i32_e32 v115, v86
	s_waitcnt lgkmcnt(4)
	v_mfma_f32_32x32x16_bf16 v[98:113], v[224:227], v[228:231], v[98:113]
	ds_read_b128 v[224:227], v219 offset:480
	ds_read_b128 v[228:231], v213 offset:480
	v_mul_f32_e32 v82, v114, v115
	s_waitcnt lgkmcnt(4)
	v_mfma_f32_32x32x16_bf16 v[98:113], v[232:235], v[236:239], v[98:113]
	ds_read_b128 v[232:235], v219 offset:16896
	ds_read_b128 v[236:239], v213
	v_exp_f32_e32 v114, v82
	s_waitcnt lgkmcnt(4)
	v_mfma_f32_32x32x16_bf16 v[98:113], v[240:243], v[244:247], v[98:113]
	ds_read_b128 v[240:243], v219 offset:16928
	ds_read_b128 v[244:247], v213 offset:32
	v_add_u32_e32 v115, s10, v216
	s_waitcnt lgkmcnt(4)
	v_mfma_f32_32x32x16_bf16 v[98:113], v[224:227], v[228:231], v[98:113]
	s_cbranch_scc1 .LBB0_431
	ds_read_b128 v[82:85], v115
	ds_read_b128 v[86:89], v115 offset:16
	ds_read_b128 v[90:93], v115 offset:32
	ds_read_b128 v[94:97], v115 offset:48
	s_waitcnt lgkmcnt(3)
	v_pk_mul_f32 v[84:85], v[114:115], v[84:85] op_sel_hi:[0,1]
	s_waitcnt lgkmcnt(2)
	v_pk_mul_f32 v[88:89], v[114:115], v[88:89] op_sel_hi:[0,1]
	s_waitcnt lgkmcnt(1)
	v_pk_mul_f32 v[92:93], v[114:115], v[92:93] op_sel_hi:[0,1]
	s_waitcnt lgkmcnt(0)
	v_pk_mul_f32 v[96:97], v[114:115], v[96:97] op_sel_hi:[0,1]
	v_pk_mul_f32 v[82:83], v[114:115], v[82:83] op_sel_hi:[0,1]
	v_pk_mul_f32 v[86:87], v[114:115], v[86:87] op_sel_hi:[0,1]
	v_pk_mul_f32 v[90:91], v[114:115], v[90:91] op_sel_hi:[0,1]
	v_pk_mul_f32 v[94:95], v[114:115], v[94:95] op_sel_hi:[0,1]
	v_pk_mul_f32 v[94:95], v[110:111], v[94:95]
	v_pk_mul_f32 v[90:91], v[106:107], v[90:91]
	v_pk_mul_f32 v[86:87], v[102:103], v[86:87]
	v_pk_mul_f32 v[96:97], v[112:113], v[96:97]
	v_pk_mul_f32 v[92:93], v[108:109], v[92:93]
	v_pk_mul_f32 v[88:89], v[104:105], v[88:89]
	v_pk_mul_f32 v[84:85], v[100:101], v[84:85]
	v_pk_mul_f32 v[82:83], v[98:99], v[82:83]
	s_cbranch_execnz .LBB0_426

.LBB0_426:
	s_andn2_b64 vcc, exec, s[86:87]
	ds_read_b128 v[224:227], v219 offset:16960
	ds_read_b128 v[228:231], v213 offset:64
	s_waitcnt lgkmcnt(4)
	v_mfma_f32_32x32x16_bf16 v[98:113], v[232:235], v[236:239], 0
	ds_read_b128 v[232:235], v219 offset:16992
	ds_read_b128 v[236:239], v213 offset:96
	s_waitcnt lgkmcnt(4)
	v_mfma_f32_32x32x16_bf16 v[98:113], v[240:243], v[244:247], v[98:113]
	ds_read_b128 v[240:243], v219 offset:17024
	ds_read_b128 v[244:247], v213 offset:128
	s_waitcnt lgkmcnt(4)
	v_mfma_f32_32x32x16_bf16 v[98:113], v[224:227], v[228:231], v[98:113]
	ds_read_b128 v[224:227], v219 offset:17056
	ds_read_b128 v[228:231], v213 offset:160
	s_waitcnt lgkmcnt(4)
	v_mfma_f32_32x32x16_bf16 v[98:113], v[232:235], v[236:239], v[98:113]
	ds_read_b128 v[232:235], v219 offset:17088
	ds_read_b128 v[236:239], v213 offset:192
	s_waitcnt lgkmcnt(4)
	v_mfma_f32_32x32x16_bf16 v[98:113], v[240:243], v[244:247], v[98:113]
	ds_read_b128 v[240:243], v219 offset:17120
	ds_read_b128 v[244:247], v213 offset:224
	s_waitcnt lgkmcnt(4)
	v_mfma_f32_32x32x16_bf16 v[98:113], v[224:227], v[228:231], v[98:113]
	ds_read_b128 v[224:227], v219 offset:17152
	ds_read_b128 v[228:231], v213 offset:256
	s_waitcnt lgkmcnt(4)
	v_mfma_f32_32x32x16_bf16 v[98:113], v[232:235], v[236:239], v[98:113]
	ds_read_b128 v[232:235], v219 offset:17184
	ds_read_b128 v[236:239], v213 offset:288
	s_waitcnt lgkmcnt(4)
	v_mfma_f32_32x32x16_bf16 v[98:113], v[240:243], v[244:247], v[98:113]
	ds_read_b128 v[240:243], v219 offset:17216
	ds_read_b128 v[244:247], v213 offset:320
	s_waitcnt lgkmcnt(4)
	v_mfma_f32_32x32x16_bf16 v[98:113], v[224:227], v[228:231], v[98:113]
	ds_read_b128 v[224:227], v219 offset:17248
	ds_read_b128 v[228:231], v213 offset:352
	s_waitcnt lgkmcnt(4)
	v_mfma_f32_32x32x16_bf16 v[98:113], v[232:235], v[236:239], v[98:113]
	ds_read_b128 v[232:235], v219 offset:17280
	ds_read_b128 v[236:239], v213 offset:384
	s_waitcnt lgkmcnt(4)
	v_mfma_f32_32x32x16_bf16 v[98:113], v[240:243], v[244:247], v[98:113]
	ds_read_b128 v[240:243], v219 offset:17312
	ds_read_b128 v[244:247], v213 offset:416
	s_waitcnt lgkmcnt(4)
	v_mfma_f32_32x32x16_bf16 v[98:113], v[224:227], v[228:231], v[98:113]
	ds_read_b128 v[224:227], v219 offset:17344
	ds_read_b128 v[228:231], v213 offset:448
	s_waitcnt lgkmcnt(4)
	v_mfma_f32_32x32x16_bf16 v[98:113], v[232:235], v[236:239], v[98:113]
	ds_read_b128 v[232:235], v219 offset:17376
	ds_read_b128 v[236:239], v213 offset:480
	s_waitcnt lgkmcnt(4)
	v_mfma_f32_32x32x16_bf16 v[98:113], v[240:243], v[244:247], v[98:113]
	s_waitcnt lgkmcnt(2)
	v_mfma_f32_32x32x16_bf16 v[98:113], v[224:227], v[228:231], v[98:113]
	s_waitcnt lgkmcnt(0)
	v_mfma_f32_32x32x16_bf16 v[98:113], v[232:235], v[236:239], v[98:113]
	v_add_u32_e32 v248, 0x1000, v220
	v_add_u32_e32 v249, 0x2000, v220
	v_add_u32_e32 v250, 0x3000, v220
	ds_read2_b64 v[240:243], v220 offset1:2
	ds_read2_b64 v[244:247], v220 offset0:4 offset1:6
	ds_read2_b64 v[224:227], v220 offset0:8 offset1:10
	ds_read2_b64 v[228:231], v220 offset0:12 offset1:14
	ds_read2_b64 v[232:235], v248 offset0:32 offset1:34
	ds_read2_b64 v[236:239], v248 offset0:36 offset1:38
	s_cbranch_vccnz .LBB0_432
	ds_read_b128 v[116:119], v115 offset:64
	ds_read_b128 v[120:123], v115 offset:80
	ds_read_b128 v[124:127], v115 offset:96
	ds_read_b128 v[184:187], v115 offset:112
	s_waitcnt lgkmcnt(3)
	v_pk_mul_f32 v[188:189], v[114:115], v[118:119] op_sel_hi:[0,1]
	s_waitcnt lgkmcnt(2)
	v_pk_mul_f32 v[190:191], v[114:115], v[122:123] op_sel_hi:[0,1]
	s_waitcnt lgkmcnt(1)
	v_pk_mul_f32 v[192:193], v[114:115], v[126:127] op_sel_hi:[0,1]
	s_waitcnt lgkmcnt(0)
	v_pk_mul_f32 v[128:129], v[114:115], v[186:187] op_sel_hi:[0,1]
	v_pk_mul_f32 v[186:187], v[114:115], v[116:117] op_sel_hi:[0,1]
	v_pk_mul_f32 v[116:117], v[114:115], v[120:121] op_sel_hi:[0,1]
	v_pk_mul_f32 v[118:119], v[114:115], v[124:125] op_sel_hi:[0,1]
	v_pk_mul_f32 v[114:115], v[114:115], v[184:185] op_sel_hi:[0,1]
	v_pk_mul_f32 v[126:127], v[110:111], v[114:115]
	v_pk_mul_f32 v[122:123], v[106:107], v[118:119]
	v_pk_mul_f32 v[118:119], v[102:103], v[116:117]
	v_pk_mul_f32 v[128:129], v[112:113], v[128:129]
	v_pk_mul_f32 v[124:125], v[108:109], v[192:193]
	v_pk_mul_f32 v[120:121], v[104:105], v[190:191]
	v_pk_mul_f32 v[116:117], v[100:101], v[188:189]
	v_pk_mul_f32 v[114:115], v[98:99], v[186:187]
	s_cbranch_execnz .LBB0_429

.LBB0_429:
	v_cvt_pk_bf16_f32 v82, v82, v83
	v_cvt_pk_bf16_f32 v83, v84, v85
	v_cvt_pk_bf16_f32 v84, v86, v87
	v_cvt_pk_bf16_f32 v85, v88, v89
	v_cvt_pk_bf16_f32 v86, v90, v91
	v_cvt_pk_bf16_f32 v87, v92, v93
	v_cvt_pk_bf16_f32 v88, v94, v95
	v_cvt_pk_bf16_f32 v89, v96, v97
	v_cvt_pk_bf16_f32 v90, v114, v115
	v_cvt_pk_bf16_f32 v91, v116, v117
	v_cvt_pk_bf16_f32 v92, v118, v119
	v_cvt_pk_bf16_f32 v93, v120, v121
	v_cvt_pk_bf16_f32 v94, v122, v123
	v_cvt_pk_bf16_f32 v95, v124, v125
	v_cvt_pk_bf16_f32 v96, v126, v127
	v_cvt_pk_bf16_f32 v97, v128, v129
	s_waitcnt lgkmcnt(5)
	v_mfma_f32_32x32x16_bf16 v[52:67], v[240:243], v[82:85], v[52:67]
	ds_read2_b64 v[240:243], v248 offset0:40 offset1:42
	s_waitcnt lgkmcnt(5)
	v_mfma_f32_32x32x16_bf16 v[52:67], v[244:247], v[86:89], v[52:67]
	ds_read2_b64 v[244:247], v248 offset0:44 offset1:46
	s_waitcnt lgkmcnt(5)
	v_mfma_f32_32x32x16_bf16 v[52:67], v[224:227], v[90:93], v[52:67]
	ds_read2_b64 v[224:227], v249 offset0:64 offset1:66
	s_waitcnt lgkmcnt(5)
	v_mfma_f32_32x32x16_bf16 v[52:67], v[228:231], v[94:97], v[52:67]
	ds_read2_b64 v[228:231], v249 offset0:68 offset1:70
	s_waitcnt lgkmcnt(5)
	v_mfma_f32_32x32x16_bf16 v[36:51], v[232:235], v[82:85], v[36:51]
	ds_read2_b64 v[232:235], v249 offset0:72 offset1:74
	s_waitcnt lgkmcnt(5)
	v_mfma_f32_32x32x16_bf16 v[36:51], v[236:239], v[86:89], v[36:51]
	ds_read2_b64 v[236:239], v249 offset0:76 offset1:78
	s_waitcnt lgkmcnt(5)
	v_mfma_f32_32x32x16_bf16 v[36:51], v[240:243], v[90:93], v[36:51]
	ds_read2_b64 v[240:243], v250 offset0:96 offset1:98
	s_waitcnt lgkmcnt(5)
	v_mfma_f32_32x32x16_bf16 v[36:51], v[244:247], v[94:97], v[36:51]
	ds_read2_b64 v[244:247], v250 offset0:100 offset1:102
	s_waitcnt lgkmcnt(5)
	v_mfma_f32_32x32x16_bf16 v[20:35], v[224:227], v[82:85], v[20:35]
	ds_read2_b64 v[224:227], v250 offset0:104 offset1:106
	s_waitcnt lgkmcnt(5)
	v_mfma_f32_32x32x16_bf16 v[20:35], v[228:231], v[86:89], v[20:35]
	ds_read2_b64 v[228:231], v250 offset0:108 offset1:110
	s_waitcnt lgkmcnt(5)
	v_mfma_f32_32x32x16_bf16 v[20:35], v[232:235], v[90:93], v[20:35]
	s_waitcnt lgkmcnt(4)
	v_mfma_f32_32x32x16_bf16 v[20:35], v[236:239], v[94:97], v[20:35]
	s_waitcnt lgkmcnt(3)
	v_mfma_f32_32x32x16_bf16 v[4:19], v[240:243], v[82:85], v[4:19]
	s_waitcnt lgkmcnt(2)
	v_mfma_f32_32x32x16_bf16 v[4:19], v[244:247], v[86:89], v[4:19]
	s_waitcnt lgkmcnt(1)
	v_mfma_f32_32x32x16_bf16 v[4:19], v[224:227], v[90:93], v[4:19]
	s_waitcnt lgkmcnt(0)
	v_mfma_f32_32x32x16_bf16 v[4:19], v[228:231], v[94:97], v[4:19]
	s_waitcnt lgkmcnt(0)
	s_barrier
	s_andn2_b64 vcc, exec, s[62:63]
	s_cbranch_vccnz .LBB0_420
	s_waitcnt vmcnt(8)
	ds_write_b128 v217, v[130:133]
	s_waitcnt vmcnt(7)
	ds_write2_b64 v218, v[134:135], v[136:137] offset1:1
	s_waitcnt vmcnt(6)
	ds_write_b128 v217, v[138:141] offset:8448
	s_waitcnt vmcnt(5)
	ds_write2_b64 v199, v[142:143], v[144:145] offset1:1
	s_waitcnt vmcnt(4)
	ds_write_b128 v217, v[146:149] offset:16896
	s_waitcnt vmcnt(3)
	ds_write2_b64 v200, v[150:151], v[152:153] offset1:1
	s_waitcnt vmcnt(2)
	ds_write_b128 v217, v[154:157] offset:25344
	s_waitcnt vmcnt(1)
	ds_write2_b64 v201, v[158:159], v[160:161] offset1:1
	s_waitcnt lgkmcnt(0)
	s_barrier
	s_branch .LBB0_420
